# mega bundle: best bundle + conversion-piece rotation + DPP/permlane exchanges + attention-loop subtract-max done with 16 v_pk_add_f32 instead of 32 v_sub_f32 (instruction selection in the VALU-bound a
# speedup vs baseline: 1.0035x; 1.0016x over previous
.LBB0_1049:
	v_pk_add_f32 v[224:225], v[80:81], v[160:161] op_sel:[0,1] op_sel_hi:[1,1] neg_lo:[0,1] neg_hi:[0,1]
	v_pk_add_f32 v[226:227], v[82:83], v[160:161] op_sel:[0,1] op_sel_hi:[1,1] neg_lo:[0,1] neg_hi:[0,1]
	v_pk_add_f32 v[228:229], v[84:85], v[160:161] op_sel:[0,1] op_sel_hi:[1,1] neg_lo:[0,1] neg_hi:[0,1]
	v_pk_add_f32 v[230:231], v[86:87], v[160:161] op_sel:[0,1] op_sel_hi:[1,1] neg_lo:[0,1] neg_hi:[0,1]
	v_pk_add_f32 v[232:233], v[88:89], v[160:161] op_sel:[0,1] op_sel_hi:[1,1] neg_lo:[0,1] neg_hi:[0,1]
	v_pk_add_f32 v[234:235], v[90:91], v[160:161] op_sel:[0,1] op_sel_hi:[1,1] neg_lo:[0,1] neg_hi:[0,1]
	v_pk_add_f32 v[236:237], v[92:93], v[160:161] op_sel:[0,1] op_sel_hi:[1,1] neg_lo:[0,1] neg_hi:[0,1]
	v_pk_add_f32 v[238:239], v[94:95], v[160:161] op_sel:[0,1] op_sel_hi:[1,1] neg_lo:[0,1] neg_hi:[0,1]
	v_exp_f32_e32 v90, v226
	v_exp_f32_e32 v91, v227
	v_exp_f32_e32 v94, v230
	v_exp_f32_e32 v95, v231
	v_exp_f32_e32 v82, v234
	v_exp_f32_e32 v86, v238
	v_exp_f32_e32 v87, v239
	v_exp_f32_e32 v83, v235
	v_exp_f32_e32 v88, v224
	v_exp_f32_e32 v89, v225
	v_exp_f32_e32 v80, v232
	v_exp_f32_e32 v81, v233
	v_pk_add_f32 v[192:193], v[94:95], v[86:87]
	v_pk_add_f32 v[194:195], v[90:91], v[82:83]
	v_pk_add_f32 v[192:193], v[194:195], v[192:193]
	v_max_f32_e32 v194, v65, v65
	v_max_f32_e32 v195, v64, v64
	v_max_f32_e32 v194, v195, v194
	v_max3_f32 v194, v194, v66, v67
	v_max3_f32 v194, v194, v68, v69
	v_exp_f32_e32 v92, v228
	v_exp_f32_e32 v93, v229
	v_exp_f32_e32 v84, v236
	v_exp_f32_e32 v85, v237
	v_max3_f32 v194, v194, v70, v71
	v_max3_f32 v194, v194, v72, v73
	v_max3_f32 v194, v194, v74, v75
	v_max3_f32 v194, v194, v76, v77
	v_pk_add_f32 v[188:189], v[92:93], v[84:85]
	v_pk_add_f32 v[190:191], v[88:89], v[80:81]
	v_max3_f32 v194, v194, v78, v79
	v_mov_b32_e32 v195, v194
	s_nop 1
	v_permlane32_swap_b32_e32 v195, v194
	v_pk_add_f32 v[188:189], v[190:191], v[188:189]
	v_add_f32_e32 v191, 0x41000000, v167
	v_pk_add_f32 v[188:189], v[188:189], v[192:193]
	s_waitcnt lgkmcnt(0)
	v_max_f32_e32 v190, v195, v195
	v_add_f32_e32 v188, v188, v189
	v_mov_b32_e32 v189, v188
	s_nop 1
	v_permlane32_swap_b32_e32 v189, v188
	v_max_f32_e32 v190, v194, v190
	v_cmp_gt_f32_e32 vcc, v190, v191
	s_cbranch_vccz .LBB0_1051
	v_max_f32_e32 v190, v190, v190
	v_max_f32_e32 v191, v167, v167
	v_max_f32_e32 v191, v191, v190
	v_sub_f32_e32 v167, v167, v191
	v_exp_f32_e32 v190, v167
	v_mov_b32_e32 v167, v191
	v_mul_f32_e32 v160, v160, v190
	v_pk_mul_f32 v[30:31], v[30:31], v[190:191] op_sel_hi:[1,0]
	v_pk_mul_f32 v[28:29], v[28:29], v[190:191] op_sel_hi:[1,0]
	v_pk_mul_f32 v[26:27], v[26:27], v[190:191] op_sel_hi:[1,0]
	v_pk_mul_f32 v[24:25], v[24:25], v[190:191] op_sel_hi:[1,0]
	v_pk_mul_f32 v[22:23], v[22:23], v[190:191] op_sel_hi:[1,0]
	v_pk_mul_f32 v[20:21], v[20:21], v[190:191] op_sel_hi:[1,0]
	v_pk_mul_f32 v[18:19], v[18:19], v[190:191] op_sel_hi:[1,0]
	v_pk_mul_f32 v[16:17], v[16:17], v[190:191] op_sel_hi:[1,0]
	v_pk_mul_f32 v[14:15], v[14:15], v[190:191] op_sel_hi:[1,0]
	v_pk_mul_f32 v[12:13], v[12:13], v[190:191] op_sel_hi:[1,0]
	v_pk_mul_f32 v[10:11], v[10:11], v[190:191] op_sel_hi:[1,0]
	v_pk_mul_f32 v[8:9], v[8:9], v[190:191] op_sel_hi:[1,0]
	v_pk_mul_f32 v[6:7], v[6:7], v[190:191] op_sel_hi:[1,0]
	v_pk_mul_f32 v[4:5], v[4:5], v[190:191] op_sel_hi:[1,0]
	v_pk_mul_f32 v[2:3], v[2:3], v[190:191] op_sel_hi:[1,0]
	v_pk_mul_f32 v[0:1], v[0:1], v[190:191] op_sel_hi:[1,0]
.LBB0_1051:
	v_pk_add_f32 v[208:209], v[64:65], v[166:167] op_sel:[0,1] op_sel_hi:[1,1] neg_lo:[0,1] neg_hi:[0,1]
	v_pk_add_f32 v[210:211], v[66:67], v[166:167] op_sel:[0,1] op_sel_hi:[1,1] neg_lo:[0,1] neg_hi:[0,1]
	v_pk_add_f32 v[212:213], v[68:69], v[166:167] op_sel:[0,1] op_sel_hi:[1,1] neg_lo:[0,1] neg_hi:[0,1]
	v_pk_add_f32 v[214:215], v[70:71], v[166:167] op_sel:[0,1] op_sel_hi:[1,1] neg_lo:[0,1] neg_hi:[0,1]
	v_pk_add_f32 v[216:217], v[72:73], v[166:167] op_sel:[0,1] op_sel_hi:[1,1] neg_lo:[0,1] neg_hi:[0,1]
	v_pk_add_f32 v[218:219], v[74:75], v[166:167] op_sel:[0,1] op_sel_hi:[1,1] neg_lo:[0,1] neg_hi:[0,1]
	v_pk_add_f32 v[220:221], v[76:77], v[166:167] op_sel:[0,1] op_sel_hi:[1,1] neg_lo:[0,1] neg_hi:[0,1]
	v_pk_add_f32 v[222:223], v[78:79], v[166:167] op_sel:[0,1] op_sel_hi:[1,1] neg_lo:[0,1] neg_hi:[0,1]
	v_lshl_add_u32 v191, v179, 1, s26
	v_add3_u32 v198, v191, v158, v178
	v_add_u32_e32 v199, 0x3000, v198
	v_exp_f32_e32 v190, v208
	ds_read2_b64 v[64:67], v199 offset0:128 offset1:130
	v_exp_f32_e32 v191, v209
	v_exp_f32_e32 v192, v210
	v_exp_f32_e32 v193, v211
	v_exp_f32_e32 v194, v212
	v_cvt_pk_bf16_f32 v70, v92, v93
	v_exp_f32_e32 v195, v213
	v_exp_f32_e32 v92, v214
	v_exp_f32_e32 v93, v215
	v_cvt_pk_bf16_f32 v68, v88, v89
	v_cvt_pk_bf16_f32 v69, v90, v91
	v_cvt_pk_bf16_f32 v71, v94, v95
	v_cvt_pk_bf16_f32 v88, v190, v191
	v_cvt_pk_bf16_f32 v89, v192, v193
	v_cvt_pk_bf16_f32 v90, v194, v195
	v_cvt_pk_bf16_f32 v91, v92, v93
	v_add_u32_e32 v198, 0x4000, v198
	s_waitcnt lgkmcnt(0)
	v_mfma_f32_32x32x16_bf16 v[48:63], v[64:67], v[68:71], v[48:63]
	v_exp_f32_e32 v196, v218
	v_mfma_f32_32x32x16_bf16 v[16:31], v[64:67], v[88:91], v[16:31]
	ds_read2_b64 v[64:67], v198 offset0:160 offset1:162
	v_exp_f32_e32 v197, v219
	v_exp_f32_e32 v74, v220
	v_exp_f32_e32 v75, v221
	s_waitcnt lgkmcnt(0)
	v_mfma_f32_32x32x16_bf16 v[32:47], v[64:67], v[68:71], v[32:47]
	v_exp_f32_e32 v94, v216
	v_exp_f32_e32 v95, v217
	ds_read2_b64 v[68:71], v199 offset0:132 offset1:134
	v_cvt_pk_bf16_f32 v73, v196, v197
	v_cvt_pk_bf16_f32 v72, v94, v95
	v_mfma_f32_32x32x16_bf16 v[0:15], v[64:67], v[88:91], v[0:15]
	v_exp_f32_e32 v88, v222
	v_exp_f32_e32 v89, v223
	ds_read2_b64 v[76:79], v198 offset0:164 offset1:166
	v_cvt_pk_bf16_f32 v64, v80, v81
	v_cvt_pk_bf16_f32 v65, v82, v83
	v_cvt_pk_bf16_f32 v66, v84, v85
	v_cvt_pk_bf16_f32 v67, v86, v87
	v_pk_add_f32 v[80:81], v[194:195], v[74:75]
	v_cvt_pk_bf16_f32 v74, v74, v75
	v_cvt_pk_bf16_f32 v75, v88, v89
	s_waitcnt lgkmcnt(1)
	v_mfma_f32_32x32x16_bf16 v[48:63], v[68:71], v[64:67], v[48:63]
	v_add_f32_e64 v82, v192, v196
	v_add_f32_e64 v83, v193, v197
	v_mfma_f32_32x32x16_bf16 v[16:31], v[68:71], v[72:75], v[16:31]
	v_add_f32_e64 v68, v190, v94
	v_add_f32_e64 v69, v191, v95
	v_add_f32_e64 v70, v92, v88
	v_add_f32_e64 v71, v93, v89
	v_add_f32_e64 v68, v68, v80
	v_add_f32_e64 v69, v69, v81
	v_pk_add_f32 v[70:71], v[82:83], v[70:71]
	s_nop 0
	v_pk_add_f32 v[68:69], v[68:69], v[70:71]
	s_nop 0
	v_add_f32_e32 v68, v68, v69
	s_waitcnt lgkmcnt(0)
	v_mfma_f32_32x32x16_bf16 v[32:47], v[76:79], v[64:67], v[32:47]
	v_mov_b32_e32 v64, v68
	s_nop 1
	v_permlane32_swap_b32_e32 v64, v68
	v_add_f32_e32 v65, v188, v189
	v_add_f32_e32 v162, v162, v65
	s_waitcnt lgkmcnt(0)
	v_add_f32_e32 v64, v68, v64
	v_add_f32_e32 v160, v160, v64
	v_mfma_f32_32x32x16_bf16 v[0:15], v[76:79], v[72:75], v[0:15]
